# conversion engine v8: each wave converts a contiguous block of items (43 + 16 consecutive 32x32 tiles) instead of a 2048-strided set (TLB / DRAM-page locality of the f32 weight loads)
# speedup vs baseline: 1.0039x; 1.0039x over previous
.LBB0_137:
	s_lshl_b32 s5, s5, 5
	s_mov_b64 s[18:19], 0x80
	s_and_b32 s5, s5, 0x60
	s_add_i32 m0, s55, 0x18000
	v_lshl_add_u64 v[8:9], v[8:9], 0, s[18:19]
	s_lshl_b32 s1, s4, 13
	s_lshl_b32 s22, s5, 7
	s_waitcnt vmcnt(2)
	s_barrier
	global_load_lds_dwordx4 v[8:9], off
	v_lshl_add_u64 v[4:5], v[4:5], 0, s[18:19]
	s_add_i32 m0, s55, 0x1a000
	s_add_i32 s75, s55, 0x8000
	s_add_i32 s76, s55, 0xa000
	global_load_lds_dwordx4 v[4:5], off
	v_lshl_add_u64 v[2:3], v[2:3], 0, s[18:19]
	s_mov_b32 m0, s75
	s_add_u32 s20, s8, 0x100080
	global_load_lds_dwordx4 v[2:3], off
	v_lshl_add_u64 v[2:3], v[6:7], 0, s[18:19]
	s_mov_b32 m0, s76
	s_addc_u32 s21, s9, 0
	global_load_lds_dwordx4 v[2:3], off
	s_add_i32 m0, s55, 0x1c000
	v_lshl_add_u64 v[2:3], s[20:21], 0, v[140:141]
	global_load_lds_dwordx4 v[2:3], off
	v_lshl_add_u64 v[2:3], s[20:21], 0, v[144:145]
	s_add_i32 m0, s55, 0x1e000
	v_and_b32_e32 v4, 32, v162
	global_load_lds_dwordx4 v[2:3], off
	v_and_b32_e32 v2, 15, v0
	v_lshlrev_b32_e32 v3, 1, v14
	v_lshl_or_b32 v163, s4, 6, v2
	v_lshl_or_b32 v2, v2, 6, v3
	v_bitop3_b32 v2, v2, s1, v4 bitop3:0xde
	v_lshlrev_b32_e32 v5, 6, v0
	s_movk_i32 s1, 0x3c0
	v_and_or_b32 v3, v5, s1, v3
	v_bitop3_b32 v164, s22, v3, v4 bitop3:0xf6
	v_lshlrev_b32_e32 v3, 10, v0
	v_and_b32_e32 v3, 0x60000, v3
	v_lshlrev_b32_e32 v4, 13, v12
	v_or3_b32 v3, v10, v3, v4
	s_cmpk_lt_u32 s14, 0x100
	v_add_u32_e32 v148, v3, v11
	v_lshlrev_b32_e32 v3, 6, v13
	s_waitcnt vmcnt(6)
	s_cselect_b64 s[20:21], -1, 0
	s_add_u32 s22, s62, 0x2000
	v_and_b32_e32 v3, 0xe0000, v3
	v_or_b32_e32 v165, s5, v14
	s_addc_u32 s23, s63, 0
	v_or3_b32 v3, v10, v3, v4
	s_add_i32 s83, 0, 0x10000
	s_add_i32 s89, 0, 0x14000
	v_or_b32_e32 v166, 0xffffec00, v165
	s_ashr_i32 s77, s74, 31
	s_ashr_i32 s81, s2, 31
	v_mov_b32_e32 v149, v147
	v_add_u32_e32 v150, v3, v11
	v_mov_b32_e32 v151, v147
	v_mov_b64_e32 v[152:153], 0x900
	v_mov_b64_e32 v[154:155], 0x8ff
	v_add_u32_e32 v167, s83, v164
	v_add_u32_e32 v168, s89, v164
	v_add_u32_e32 v169, 0, v2
	s_mov_b32 s90, 0xc2a00000
	s_mov_b32 s91, 0xc1f00000
	v_mov_b32_e32 v170, 0x42a00000
	v_mov_b32_e32 v171, 0x41f00000
	s_mov_b32 s92, 0
	s_barrier
	s_bfe_u32 s32, s2, 0x20003
	s_sub_i32 s32, 0, s32
	s_mov_b32 s97, 0
	v_readlane_b32 s98, v244, 0
	v_readlane_b32 s99, v244, 1
	s_nop 3
	s_sub_u32 s98, s98, 0x98
	s_subb_u32 s99, s99, 0
	s_load_dwordx2 s[100:101], s[98:99], 0x58
	s_waitcnt lgkmcnt(0)
	v_writelane_b32 v245, s100, 0
	v_writelane_b32 v245, s101, 1
	s_nop 1
	s_load_dwordx2 s[100:101], s[98:99], 0x60
	s_waitcnt lgkmcnt(0)
	v_writelane_b32 v245, s100, 2
	v_writelane_b32 v245, s101, 3
	s_nop 1
	s_load_dwordx2 s[100:101], s[98:99], 0x50
	s_waitcnt lgkmcnt(0)
	v_writelane_b32 v245, s100, 4
	v_writelane_b32 v245, s101, 5
	s_nop 1
	s_load_dwordx2 s[100:101], s[98:99], 0x38
	s_waitcnt lgkmcnt(0)
	v_writelane_b32 v245, s100, 6
	v_writelane_b32 v245, s101, 7
	s_nop 1
	s_load_dwordx2 s[100:101], s[98:99], 0x40
	s_waitcnt lgkmcnt(0)
	v_writelane_b32 v245, s100, 8
	v_writelane_b32 v245, s101, 9
	s_nop 1
	s_load_dwordx2 s[100:101], s[98:99], 0x48
	s_waitcnt lgkmcnt(0)
	v_writelane_b32 v245, s100, 10
	v_writelane_b32 v245, s101, 11
	s_mul_i32 s98, s80, 43
	s_mul_hi_u32 s93, s98, 0xbe82fa0c
	s_lshr_b32 s93, s93, 8
	s_mul_i32 s85, s93, 0x158
	s_sub_i32 s85, s98, s85
	s_lshl_b32 s93, s93, 16
	s_or_b32 s85, s85, s93
	s_mov_b64 s[100:101], 0
	s_branch .LBB0_140

.Leng_adv:
	s_cmp_lg_u32 s93, 3
	s_cbranch_scc1 .Leng_done
	s_lshr_b32 s93, s32, 2
	s_bitcmp1_b32 s85, 31
	s_cbranch_scc0 .Leng_advA
	s_add_i32 s85, s85, 1
	s_cmp_ge_u32 s93, 59
	s_cbranch_scc0 .Leng_done
	s_mov_b32 s85, 0x80008000
	s_branch .Leng_done
.Leng_advA:
	s_add_i32 s85, s85, 1
	s_and_b32 s98, s85, 0xffff
	s_cmp_ge_u32 s98, 0x158
	s_cbranch_scc0 .Leng_advA2
	s_add_i32 s85, s85, 0xfea8
.Leng_advA2:
	s_cmp_ge_u32 s93, 43
	s_cbranch_scc0 .Leng_done
	s_lshl_b32 s85, s80, 4
	s_or_b32 s85, s85, 0x80000000
